# compress loop: counted vmcnt waits on the path where the next half-step loads are in flight (no full drain per iteration)
# baseline (speedup 1.0000x reference)
; template <bool SAMPLE>
; __device__ __forceinline__ void compress_unit(Frame& F, int l, int unit) {
;     ...
;     CMP_LOAD(0, w * 8);
; #pragma unroll 1
;     for (int li = 0; li < 8; ++li) { const int lpos = w * 8 + li;
;         CMP_LOAD(1, lpos); __builtin_amdgcn_sched_barrier(0);
;         CMP_MMA(0); __builtin_amdgcn_sched_barrier(0);
;         if (li < 7) CMP_LOAD(0, lpos + 1);
;         __builtin_amdgcn_sched_barrier(0);
;         CMP_MMA(1); __builtin_amdgcn_sched_barrier(0);
;     }
.LBB0_577:
	s_mov_b32 s22, 0x7e000
	v_add_co_u32_e32 v136, vcc, s22, v224
	s_mov_b32 s22, 0x7f000
	s_nop 0
	v_addc_co_u32_e32 v137, vcc, 0, v225, vcc
	v_add_co_u32_e32 v144, vcc, s22, v224
	v_lshl_add_u64 v[228:229], v[220:221], 0, s[66:67]
	s_nop 0
	v_addc_co_u32_e32 v145, vcc, 0, v225, vcc
	v_lshl_add_u64 v[226:227], v[222:223], 0, s[66:67]
	global_load_dwordx4 v[188:191], v[228:229], off offset:1040
	global_load_dwordx4 v[192:195], v[228:229], off offset:1024
	global_load_dwordx4 v[176:179], v[226:227], off offset:1040
	global_load_dwordx4 v[184:187], v[226:227], off offset:1024
	global_load_dwordx4 v[156:159], v[136:137], off offset:2048
	global_load_dwordx4 v[132:135], v[136:137], off offset:64
	global_load_dwordx4 v[164:167], v[144:145], off offset:-4096
	s_nop 0
	global_load_dwordx4 v[136:139], v[136:137], off offset:2112
	s_nop 0
	global_load_dwordx4 v[168:171], v[144:145], off
	global_load_dwordx4 v[140:143], v[144:145], off offset:64
	global_load_dwordx4 v[172:175], v[144:145], off offset:2048
	s_nop 0
	global_load_dwordx4 v[144:147], v[144:145], off offset:2112
	s_nop 0
	global_load_dwordx4 v[160:163], v[228:229], off offset:1168
	global_load_dwordx4 v[180:183], v[228:229], off offset:1152
	global_load_dwordx4 v[148:151], v[226:227], off offset:1168
	global_load_dwordx4 v[152:155], v[226:227], off offset:1152
	s_waitcnt vmcnt(22)
	v_cvt_pk_bf16_f32 v246, v18, v19
	v_cvt_pk_bf16_f32 v247, v20, v21
	v_cvt_pk_bf16_f32 v248, v14, v15
	v_cvt_pk_bf16_f32 v249, v16, v17
	s_nop 1
	v_mfma_f32_16x16x32_bf16 v[34:37], v[2:5], v[246:249], v[34:37]
	v_mfma_f32_16x16x32_bf16 v[50:53], v[26:29], v[246:249], v[50:53]
	v_mfma_f32_16x16x32_bf16 v[58:61], v[6:9], v[246:249], v[58:61]
	v_mfma_f32_16x16x32_bf16 v[62:65], v[10:13], v[246:249], v[62:65]
	s_waitcnt vmcnt(19)
	v_cvt_pk_bf16_f32 v246, v82, v83
	v_cvt_pk_bf16_f32 v247, v84, v85
	v_cvt_pk_bf16_f32 v248, v46, v47
	v_cvt_pk_bf16_f32 v249, v48, v49
	s_nop 1
	v_mfma_f32_16x16x32_bf16 v[66:69], v[2:5], v[246:249], v[66:69]
	v_mfma_f32_16x16x32_bf16 v[70:73], v[26:29], v[246:249], v[70:73]
	v_mfma_f32_16x16x32_bf16 v[74:77], v[6:9], v[246:249], v[74:77]
	v_mfma_f32_16x16x32_bf16 v[78:81], v[10:13], v[246:249], v[78:81]
	s_waitcnt vmcnt(17)
	v_cvt_pk_bf16_f32 v246, v54, v55
	v_cvt_pk_bf16_f32 v247, v56, v57
	v_cvt_pk_bf16_f32 v248, v90, v91
	v_cvt_pk_bf16_f32 v249, v92, v93
	s_nop 1
	v_mfma_f32_16x16x32_bf16 v[34:37], v[22:25], v[246:249], v[34:37]
	v_mfma_f32_16x16x32_bf16 v[50:53], v[30:33], v[246:249], v[50:53]
	v_mfma_f32_16x16x32_bf16 v[58:61], v[38:41], v[246:249], v[58:61]
	v_mfma_f32_16x16x32_bf16 v[62:65], v[42:45], v[246:249], v[62:65]
	s_waitcnt vmcnt(16)
	v_cvt_pk_bf16_f32 v246, v120, v121
	v_cvt_pk_bf16_f32 v247, v122, v123
	v_cvt_pk_bf16_f32 v248, v128, v129
	v_cvt_pk_bf16_f32 v249, v130, v131
	s_nop 1
	v_mfma_f32_16x16x32_bf16 v[66:69], v[22:25], v[246:249], v[66:69]
	v_mfma_f32_16x16x32_bf16 v[70:73], v[30:33], v[246:249], v[70:73]
	v_mfma_f32_16x16x32_bf16 v[74:77], v[38:41], v[246:249], v[74:77]
	v_mfma_f32_16x16x32_bf16 v[78:81], v[42:45], v[246:249], v[78:81]
	s_cmpk_eq_i32 s66, 0x7000
	s_cbranch_scc1 .LBB0_576
	v_add_co_u32_e32 v42, vcc, 0x1000, v224
	v_lshl_add_u64 v[2:3], v[228:229], 0, s[96:97]
	s_nop 0
	v_addc_co_u32_e32 v43, vcc, 0, v225, vcc
	v_add_co_u32_e32 v54, vcc, 0x1000, v228
	v_lshl_add_u64 v[46:47], v[226:227], 0, s[96:97]
	s_nop 0
	v_addc_co_u32_e32 v55, vcc, 0, v229, vcc
	global_load_dwordx4 v[18:21], v[54:55], off
	global_load_dwordx4 v[14:17], v[2:3], off offset:16
	s_nop 0
	global_load_dwordx4 v[2:5], v[224:225], off
	global_load_dwordx4 v[22:25], v[224:225], off offset:64
	global_load_dwordx4 v[26:29], v[224:225], off offset:2048
	global_load_dwordx4 v[30:33], v[224:225], off offset:2112
	global_load_dwordx4 v[6:9], v[42:43], off
	global_load_dwordx4 v[38:41], v[42:43], off offset:64
	global_load_dwordx4 v[10:13], v[42:43], off offset:2048
	s_nop 0
	global_load_dwordx4 v[42:45], v[42:43], off offset:2112
	v_add_co_u32_e32 v90, vcc, 0x1000, v226
	v_lshl_add_u64 v[92:93], v[228:229], 0, s[6:7]
	s_nop 0
	v_addc_co_u32_e32 v91, vcc, 0, v227, vcc
	v_lshl_add_u64 v[128:129], v[226:227], 0, s[6:7]
	global_load_dwordx4 v[46:49], v[46:47], off offset:16
	s_nop 0
	global_load_dwordx4 v[54:57], v[54:55], off offset:128
	s_nop 0
	global_load_dwordx4 v[82:85], v[90:91], off
	global_load_dwordx4 v[120:123], v[90:91], off offset:128
	s_nop 0
	global_load_dwordx4 v[90:93], v[92:93], off offset:16
	s_nop 0
	global_load_dwordx4 v[128:131], v[128:129], off offset:16
	s_waitcnt vmcnt(30)
	v_cvt_pk_bf16_f32 v192, v192, v193
	v_cvt_pk_bf16_f32 v193, v194, v195
	v_cvt_pk_bf16_f32 v194, v188, v189
	v_cvt_pk_bf16_f32 v195, v190, v191
	s_waitcnt vmcnt(28)
	v_cvt_pk_bf16_f32 v184, v184, v185
	v_cvt_pk_bf16_f32 v185, v186, v187
	v_cvt_pk_bf16_f32 v186, v176, v177
	v_cvt_pk_bf16_f32 v187, v178, v179
	s_waitcnt vmcnt(25)
	v_mfma_f32_16x16x32_bf16 v[86:89], v[164:167], v[192:195], v[86:89]
	s_waitcnt vmcnt(16)
	v_cvt_pk_bf16_f32 v152, v152, v153
	v_cvt_pk_bf16_f32 v153, v154, v155
	v_cvt_pk_bf16_f32 v154, v148, v149
	v_mfma_f32_16x16x32_bf16 v[94:97], v[156:159], v[192:195], v[94:97]
	v_cvt_pk_bf16_f32 v155, v150, v151
	v_mfma_f32_16x16x32_bf16 v[100:103], v[168:171], v[192:195], v[100:103]
	v_mfma_f32_16x16x32_bf16 v[104:107], v[172:175], v[192:195], v[104:107]
	v_mfma_f32_16x16x32_bf16 v[108:111], v[164:167], v[184:187], v[108:111]
	v_mfma_f32_16x16x32_bf16 v[112:115], v[156:159], v[184:187], v[112:115]
	v_cvt_pk_bf16_f32 v156, v180, v181
	v_cvt_pk_bf16_f32 v157, v182, v183
	v_cvt_pk_bf16_f32 v158, v160, v161
	v_mfma_f32_16x16x32_bf16 v[116:119], v[168:171], v[184:187], v[116:119]
	v_cvt_pk_bf16_f32 v159, v162, v163
	v_mfma_f32_16x16x32_bf16 v[124:127], v[172:175], v[184:187], v[124:127]
	s_nop 0
	v_mfma_f32_16x16x32_bf16 v[86:89], v[132:135], v[156:159], v[86:89]
	v_mfma_f32_16x16x32_bf16 v[94:97], v[136:139], v[156:159], v[94:97]
	v_mfma_f32_16x16x32_bf16 v[100:103], v[140:143], v[156:159], v[100:103]
	v_mfma_f32_16x16x32_bf16 v[104:107], v[144:147], v[156:159], v[104:107]
	v_mfma_f32_16x16x32_bf16 v[108:111], v[132:135], v[152:155], v[108:111]
	v_mfma_f32_16x16x32_bf16 v[112:115], v[136:139], v[152:155], v[112:115]
	v_mfma_f32_16x16x32_bf16 v[116:119], v[140:143], v[152:155], v[116:119]
	v_mfma_f32_16x16x32_bf16 v[124:127], v[144:147], v[152:155], v[124:127]
	s_add_u32 s66, s66, 0x1000
	s_addc_u32 s67, s67, 0
	s_cmpk_eq_u32 s66, 0x8000
	v_lshl_add_u64 v[224:225], v[224:225], 0, s[94:95]
	s_branch .LBB0_577
